# GEMM4 epilogue: residual loads of all four row groups issued before one wait, store groups no longer wait for the previous group's store acks
# speedup vs baseline: 1.0047x; 1.0047x over previous
;     __device__ __forceinline__ void operator()(const f32x4 (&acc)[2][2][4][2], const Unit& u, int wr, int wc, int fr, int fq) const {
;     ...
;         const bf16_t* H1B = (const bf16_t*)(ws + WS_XB); float* yp = out + O_YP;
; #pragma unroll
;         for (int ai = 0; ai < 2; ++ai) { u32x2 hw[4][2][2];
; #pragma unroll
;             for (int m = 0; m < 4; ++m)
; #pragma unroll
;                 for (int bj = 0; bj < 2; ++bj)
; #pragma unroll
;                     for (int n = 0; n < 2; ++n) hw[m][bj][n] = *(const u32x2*)(H1B + (size_t)(row0 + ai * HALF + m * 16) * 4096 + col0 + bj * HALF + n * 16);
; #pragma unroll
;             for (int m = 0; m < 4; ++m) { const int row = row0 + ai * HALF + m * 16;
;                 float* dst = (row >= 272 && row < G_MV) ? yp + (size_t)(row - 272) * 4096 : nullptr;
;                 if (dst) {
; #pragma unroll
;                     for (int bj = 0; bj < 2; ++bj)
; #pragma unroll
;                         for (int n = 0; n < 2; ++n) { const int c = col0 + bj * HALF + n * 16; const u32x2 w = hw[m][bj][n]; f32x4 h;
;                             h[0] = __builtin_bit_cast(float, w.x << 16); h[1] = __builtin_bit_cast(float, w.x & 0xffff0000u); h[2] = __builtin_bit_cast(float, w.y << 16); h[3] = __builtin_bit_cast(float, w.y & 0xffff0000u);
;                             *(f32x4*)(dst + c) = h + acc[ai][bj][m][n]; } } } }
.LBB0_3526:
	v_lshl_add_u32 v146, s4, 8, v136
	v_or_b32_e32 v150, 16, v146
	v_ashrrev_i32_e32 v145, 31, v144
	v_ashrrev_i32_e32 v151, 31, v150
	v_lshl_add_u64 v[148:149], v[144:145], 1, s[10:11]
	v_lshlrev_b64 v[150:151], 13, v[150:151]
	v_lshl_add_u64 v[150:151], v[148:149], 0, v[150:151]
	global_load_dwordx2 v[174:175], v[150:151], off
	global_load_dwordx2 v[172:173], v[150:151], off offset:32
	global_load_dwordx2 v[170:171], v[150:151], off offset:256
	global_load_dwordx2 v[168:169], v[150:151], off offset:288
	v_or_b32_e32 v150, 32, v146
	v_ashrrev_i32_e32 v151, 31, v150
	v_lshlrev_b64 v[150:151], 13, v[150:151]
	v_lshl_add_u64 v[150:151], v[148:149], 0, v[150:151]
	global_load_dwordx2 v[166:167], v[150:151], off
	global_load_dwordx2 v[164:165], v[150:151], off offset:32
	global_load_dwordx2 v[162:163], v[150:151], off offset:256
	global_load_dwordx2 v[160:161], v[150:151], off offset:288
	v_or_b32_e32 v150, 48, v146
	v_ashrrev_i32_e32 v151, 31, v150
	v_lshlrev_b64 v[150:151], 13, v[150:151]
	v_lshl_add_u64 v[150:151], v[148:149], 0, v[150:151]
	global_load_dwordx2 v[158:159], v[150:151], off
	global_load_dwordx2 v[156:157], v[150:151], off offset:32
	global_load_dwordx2 v[154:155], v[150:151], off offset:256
	global_load_dwordx2 v[152:153], v[150:151], off offset:288
	v_add_u32_e32 v134, 0xfffffef0, v146
	v_cmp_gt_u32_e32 vcc, s55, v134
	s_and_b64 s[4:5], vcc, s[22:23]
	v_lshlrev_b32_e32 v150, 13, v146
	v_mov_b32_e32 v151, v135
	v_lshl_add_u64 v[180:181], v[148:149], 0, v[150:151]
	global_load_dwordx2 v[182:183], v[180:181], off
	global_load_dwordx2 v[184:185], v[180:181], off offset:32
	global_load_dwordx2 v[186:187], v[180:181], off offset:256
	s_nop 0
	global_load_dwordx2 v[180:181], v[180:181], off offset:288
	s_waitcnt vmcnt(0)
	s_and_saveexec_b64 s[38:39], s[4:5]
	s_cbranch_execz .LBB0_3528
	v_lshlrev_b32_e32 v134, 14, v134
	v_lshl_add_u64 v[188:189], s[8:9], 0, v[134:135]
	v_lshl_add_u64 v[188:189], v[144:145], 2, v[188:189]
	v_lshlrev_b32_e32 v190, 16, v182
	v_and_b32_e32 v191, 0xffff0000, v182
	v_lshlrev_b32_e32 v182, 16, v183
	v_and_b32_e32 v183, 0xffff0000, v183
	v_lshlrev_b32_e32 v192, 16, v184
	v_and_b32_e32 v193, 0xffff0000, v184
	v_lshlrev_b32_e32 v184, 16, v185
	v_and_b32_e32 v185, 0xffff0000, v185
	v_lshlrev_b32_e32 v194, 16, v186
	v_and_b32_e32 v195, 0xffff0000, v186
	v_lshlrev_b32_e32 v186, 16, v187
	v_and_b32_e32 v187, 0xffff0000, v187
	v_lshlrev_b32_e32 v196, 16, v180
	v_and_b32_e32 v197, 0xffff0000, v180
	v_lshlrev_b32_e32 v180, 16, v181
	v_and_b32_e32 v181, 0xffff0000, v181
	v_pk_add_f32 v[128:129], v[128:129], v[182:183]
	v_pk_add_f32 v[126:127], v[126:127], v[190:191]
	v_pk_add_f32 v[124:125], v[124:125], v[184:185]
	v_pk_add_f32 v[122:123], v[122:123], v[192:193]
	v_pk_add_f32 v[120:121], v[120:121], v[186:187]
	v_pk_add_f32 v[118:119], v[118:119], v[194:195]
	v_pk_add_f32 v[116:117], v[116:117], v[180:181]
	v_pk_add_f32 v[114:115], v[114:115], v[196:197]
	global_store_dwordx4 v[188:189], v[126:129], off
	global_store_dwordx4 v[188:189], v[122:125], off offset:64
	global_store_dwordx4 v[188:189], v[118:121], off offset:512
	global_store_dwordx4 v[188:189], v[114:117], off offset:576
.LBB0_3528:
	s_or_b64 exec, exec, s[38:39]
	s_nop 0
	v_add_u32_e32 v114, 0xffffff00, v146
	v_cmp_gt_u32_e32 vcc, s55, v114
	s_and_b64 s[4:5], vcc, s[22:23]
	s_and_saveexec_b64 s[38:39], s[4:5]
	s_cbranch_execz .LBB0_3530
	v_lshlrev_b32_e32 v134, 14, v114
	v_lshl_add_u64 v[114:115], s[8:9], 0, v[134:135]
	v_lshlrev_b32_e32 v116, 16, v174
	v_and_b32_e32 v117, 0xffff0000, v174
	v_lshlrev_b32_e32 v118, 16, v175
	v_and_b32_e32 v119, 0xffff0000, v175
	v_pk_add_f32 v[112:113], v[112:113], v[118:119]
	v_pk_add_f32 v[110:111], v[110:111], v[116:117]
	v_lshl_add_u64 v[114:115], v[144:145], 2, v[114:115]
	global_store_dwordx4 v[114:115], v[110:113], off
	s_nop 1
	v_lshlrev_b32_e32 v110, 16, v172
	v_and_b32_e32 v111, 0xffff0000, v172
	v_lshlrev_b32_e32 v112, 16, v173
	v_and_b32_e32 v113, 0xffff0000, v173
	v_pk_add_f32 v[108:109], v[108:109], v[112:113]
	v_pk_add_f32 v[106:107], v[106:107], v[110:111]
	global_store_dwordx4 v[114:115], v[106:109], off offset:64
	s_nop 1
	v_lshlrev_b32_e32 v106, 16, v170
	v_and_b32_e32 v107, 0xffff0000, v170
	v_lshlrev_b32_e32 v108, 16, v171
	v_and_b32_e32 v109, 0xffff0000, v171
	v_pk_add_f32 v[104:105], v[104:105], v[108:109]
	v_pk_add_f32 v[102:103], v[102:103], v[106:107]
	global_store_dwordx4 v[114:115], v[102:105], off offset:512
	s_nop 1
	v_lshlrev_b32_e32 v102, 16, v168
	v_and_b32_e32 v103, 0xffff0000, v168
	v_lshlrev_b32_e32 v104, 16, v169
	v_and_b32_e32 v105, 0xffff0000, v169
	v_pk_add_f32 v[100:101], v[100:101], v[104:105]
	v_pk_add_f32 v[98:99], v[98:99], v[102:103]
	global_store_dwordx4 v[114:115], v[98:101], off offset:576
.LBB0_3530:
	s_or_b64 exec, exec, s[38:39]
	s_nop 0
	v_add_u32_e32 v98, 0xffffff10, v146
	v_cmp_gt_u32_e32 vcc, s55, v98
	s_and_b64 s[4:5], vcc, s[22:23]
	s_and_saveexec_b64 s[38:39], s[4:5]
	s_cbranch_execz .LBB0_3532
	v_lshlrev_b32_e32 v134, 14, v98
	v_lshl_add_u64 v[98:99], s[8:9], 0, v[134:135]
	v_lshlrev_b32_e32 v100, 16, v166
	v_and_b32_e32 v101, 0xffff0000, v166
	v_lshlrev_b32_e32 v102, 16, v167
	v_and_b32_e32 v103, 0xffff0000, v167
	v_pk_add_f32 v[96:97], v[96:97], v[102:103]
	v_pk_add_f32 v[94:95], v[94:95], v[100:101]
	v_lshl_add_u64 v[98:99], v[144:145], 2, v[98:99]
	global_store_dwordx4 v[98:99], v[94:97], off
	s_nop 1
	v_lshlrev_b32_e32 v94, 16, v164
	v_and_b32_e32 v95, 0xffff0000, v164
	v_lshlrev_b32_e32 v96, 16, v165
	v_and_b32_e32 v97, 0xffff0000, v165
	v_pk_add_f32 v[92:93], v[92:93], v[96:97]
	v_pk_add_f32 v[90:91], v[90:91], v[94:95]
	global_store_dwordx4 v[98:99], v[90:93], off offset:64
	s_nop 1
	v_lshlrev_b32_e32 v90, 16, v162
	v_and_b32_e32 v91, 0xffff0000, v162
	v_lshlrev_b32_e32 v92, 16, v163
	v_and_b32_e32 v93, 0xffff0000, v163
	v_pk_add_f32 v[88:89], v[88:89], v[92:93]
	v_pk_add_f32 v[86:87], v[86:87], v[90:91]
	global_store_dwordx4 v[98:99], v[86:89], off offset:512
	s_nop 1
	v_lshlrev_b32_e32 v86, 16, v160
	v_and_b32_e32 v87, 0xffff0000, v160
	v_lshlrev_b32_e32 v88, 16, v161
	v_and_b32_e32 v89, 0xffff0000, v161
	v_pk_add_f32 v[84:85], v[84:85], v[88:89]
	v_pk_add_f32 v[82:83], v[82:83], v[86:87]
	global_store_dwordx4 v[98:99], v[82:85], off offset:576
;     __device__ __forceinline__ void operator()(const f32x4 (&acc)[2][2][4][2], const Unit& u, int wr, int wc, int fr, int fq) const {
;     ...
;         for (int ai = 0; ai < 2; ++ai) { u32x2 hw[4][2][2];
; #pragma unroll
;             for (int m = 0; m < 4; ++m)
; #pragma unroll
;                 for (int bj = 0; bj < 2; ++bj)
; #pragma unroll
;                     for (int n = 0; n < 2; ++n) hw[m][bj][n] = *(const u32x2*)(H1B + (size_t)(row0 + ai * HALF + m * 16) * 4096 + col0 + bj * HALF + n * 16);
;     ...
;             for (int m = 0; m < 4; ++m) { const int row = row0 + ai * HALF + m * 16;
;                 float* dst = (row >= 272 && row < G_MV) ? yp + (size_t)(row - 272) * 4096 : nullptr;
;                 if (dst) {
; #pragma unroll
;                     for (int bj = 0; bj < 2; ++bj)
; #pragma unroll
;                         for (int n = 0; n < 2; ++n) { const int c = col0 + bj * HALF + n * 16; const u32x2 w = hw[m][bj][n]; f32x4 h;
;                             h[0] = __builtin_bit_cast(float, w.x << 16); h[1] = __builtin_bit_cast(float, w.x & 0xffff0000u); h[2] = __builtin_bit_cast(float, w.y << 16); h[3] = __builtin_bit_cast(float, w.y & 0xffff0000u);
;                             *(f32x4*)(dst + c) = h + acc[ai][bj][m][n]; } } } }
.LBB0_3532:
	s_or_b64 exec, exec, s[38:39]
	s_nop 0
	v_add_u32_e32 v82, 0xffffff20, v146
	v_cmp_gt_u32_e32 vcc, s55, v82
	s_and_b64 s[4:5], vcc, s[22:23]
	s_and_saveexec_b64 s[38:39], s[4:5]
	s_cbranch_execz .LBB0_3534
	v_lshlrev_b32_e32 v134, 14, v82
	v_lshl_add_u64 v[82:83], s[8:9], 0, v[134:135]
	v_lshlrev_b32_e32 v84, 16, v158
	v_and_b32_e32 v85, 0xffff0000, v158
	v_lshlrev_b32_e32 v86, 16, v159
	v_and_b32_e32 v87, 0xffff0000, v159
	v_pk_add_f32 v[80:81], v[80:81], v[86:87]
	v_pk_add_f32 v[78:79], v[78:79], v[84:85]
	v_lshl_add_u64 v[82:83], v[144:145], 2, v[82:83]
	global_store_dwordx4 v[82:83], v[78:81], off
	s_nop 1
	v_lshlrev_b32_e32 v78, 16, v156
	v_and_b32_e32 v79, 0xffff0000, v156
	v_lshlrev_b32_e32 v80, 16, v157
	v_and_b32_e32 v81, 0xffff0000, v157
	v_pk_add_f32 v[76:77], v[76:77], v[80:81]
	v_pk_add_f32 v[74:75], v[74:75], v[78:79]
	global_store_dwordx4 v[82:83], v[74:77], off offset:64
	s_nop 1
	v_lshlrev_b32_e32 v74, 16, v154
	v_and_b32_e32 v75, 0xffff0000, v154
	v_lshlrev_b32_e32 v76, 16, v155
	v_and_b32_e32 v77, 0xffff0000, v155
	v_pk_add_f32 v[72:73], v[72:73], v[76:77]
	v_pk_add_f32 v[70:71], v[70:71], v[74:75]
	global_store_dwordx4 v[82:83], v[70:73], off offset:512
	s_nop 1
	v_lshlrev_b32_e32 v70, 16, v152
	v_and_b32_e32 v71, 0xffff0000, v152
	v_lshlrev_b32_e32 v72, 16, v153
	v_and_b32_e32 v73, 0xffff0000, v153
	v_pk_add_f32 v[68:69], v[68:69], v[72:73]
	v_pk_add_f32 v[66:67], v[66:67], v[70:71]
	global_store_dwordx4 v[82:83], v[66:69], off offset:576
.LBB0_3534:
	s_or_b64 exec, exec, s[38:39]
	v_ashrrev_i32_e32 v147, 31, v146
	v_lshlrev_b64 v[66:67], 13, v[146:147]
	v_lshl_add_u64 v[66:67], v[148:149], 0, v[66:67]
	v_add_co_u32_e32 v70, vcc, 0x120000, v66
	v_lshl_add_u64 v[68:69], v[66:67], 0, s[24:25]
	s_nop 0
	v_addc_co_u32_e32 v71, vcc, 0, v67, vcc
	global_load_dwordx2 v[88:89], v[70:71], off
	global_load_dwordx2 v[86:87], v[68:69], off offset:32
	global_load_dwordx2 v[84:85], v[68:69], off offset:256
	global_load_dwordx2 v[82:83], v[68:69], off offset:288
	v_add_co_u32_e32 v70, vcc, 0x140000, v66
	v_lshl_add_u64 v[68:69], v[66:67], 0, s[26:27]
	s_nop 0
	v_addc_co_u32_e32 v71, vcc, 0, v67, vcc
	v_lshl_add_u64 v[90:91], v[66:67], 0, s[28:29]
	v_add_co_u32_e32 v66, vcc, 0x160000, v66
	global_load_dwordx2 v[80:81], v[70:71], off
	global_load_dwordx2 v[78:79], v[68:69], off offset:32
	global_load_dwordx2 v[76:77], v[68:69], off offset:256
	global_load_dwordx2 v[74:75], v[68:69], off offset:288
	v_addc_co_u32_e32 v67, vcc, 0, v67, vcc
	global_load_dwordx2 v[72:73], v[66:67], off
	global_load_dwordx2 v[70:71], v[90:91], off offset:32
	global_load_dwordx2 v[68:69], v[90:91], off offset:256
	s_nop 0
	global_load_dwordx2 v[66:67], v[90:91], off offset:288
	v_add_u32_e32 v90, 0xffffff70, v146
	v_cmp_gt_u32_e32 vcc, s55, v90
	s_and_b64 s[4:5], vcc, s[22:23]
	v_mov_b32_e32 v151, v135
	v_lshl_add_u64 v[92:93], v[148:149], 0, v[150:151]
	v_add_co_u32_e32 v92, vcc, 0x100000, v92
	v_lshlrev_b32_e32 v134, 14, v90
	s_nop 0
	v_addc_co_u32_e32 v93, vcc, 0, v93, vcc
	global_load_dwordx2 v[94:95], v[92:93], off
	global_load_dwordx2 v[96:97], v[92:93], off offset:32
	global_load_dwordx2 v[98:99], v[92:93], off offset:256
	s_nop 0
	global_load_dwordx2 v[92:93], v[92:93], off offset:288
	s_waitcnt vmcnt(0)
	s_and_saveexec_b64 s[38:39], s[4:5]
	s_cbranch_execz .LBB0_3536
	v_lshl_add_u64 v[90:91], s[8:9], 0, v[134:135]
	v_lshl_add_u64 v[90:91], v[144:145], 2, v[90:91]
	v_lshlrev_b32_e32 v100, 16, v94
	v_and_b32_e32 v101, 0xffff0000, v94
	v_lshlrev_b32_e32 v94, 16, v95
	v_and_b32_e32 v95, 0xffff0000, v95
	v_lshlrev_b32_e32 v102, 16, v96
	v_and_b32_e32 v103, 0xffff0000, v96
	v_lshlrev_b32_e32 v96, 16, v97
	v_and_b32_e32 v97, 0xffff0000, v97
	v_lshlrev_b32_e32 v104, 16, v98
	v_and_b32_e32 v105, 0xffff0000, v98
	v_lshlrev_b32_e32 v98, 16, v99
	v_and_b32_e32 v99, 0xffff0000, v99
	v_lshlrev_b32_e32 v106, 16, v92
	v_and_b32_e32 v107, 0xffff0000, v92
	v_lshlrev_b32_e32 v92, 16, v93
	v_and_b32_e32 v93, 0xffff0000, v93
	v_pk_add_f32 v[64:65], v[64:65], v[94:95]
	v_pk_add_f32 v[62:63], v[62:63], v[100:101]
	v_pk_add_f32 v[60:61], v[60:61], v[96:97]
	v_pk_add_f32 v[58:59], v[58:59], v[102:103]
	v_pk_add_f32 v[56:57], v[56:57], v[98:99]
	v_pk_add_f32 v[54:55], v[54:55], v[104:105]
	v_pk_add_f32 v[52:53], v[52:53], v[92:93]
	v_pk_add_f32 v[50:51], v[50:51], v[106:107]
	global_store_dwordx4 v[90:91], v[62:65], off
	global_store_dwordx4 v[90:91], v[58:61], off offset:64
	global_store_dwordx4 v[90:91], v[54:57], off offset:512
	global_store_dwordx4 v[90:91], v[50:53], off offset:576
;     __device__ __forceinline__ void operator()(const f32x4 (&acc)[2][2][4][2], const Unit& u, int wr, int wc, int fr, int fq) const {
;     ...
;             for (int m = 0; m < 4; ++m) { const int row = row0 + ai * HALF + m * 16;
;                 float* dst = (row >= 272 && row < G_MV) ? yp + (size_t)(row - 272) * 4096 : nullptr;
;                 if (dst) {
; #pragma unroll
;                     for (int bj = 0; bj < 2; ++bj)
; #pragma unroll
;                         for (int n = 0; n < 2; ++n) { const int c = col0 + bj * HALF + n * 16; const u32x2 w = hw[m][bj][n]; f32x4 h;
;                             h[0] = __builtin_bit_cast(float, w.x << 16); h[1] = __builtin_bit_cast(float, w.x & 0xffff0000u); h[2] = __builtin_bit_cast(float, w.y << 16); h[3] = __builtin_bit_cast(float, w.y & 0xffff0000u);
;                             *(f32x4*)(dst + c) = h + acc[ai][bj][m][n]; } } } }
.LBB0_3536:
	s_or_b64 exec, exec, s[38:39]
	s_nop 0
	v_add_u32_e32 v50, 0xffffff80, v146
	v_cmp_gt_u32_e32 vcc, s55, v50
	s_and_b64 s[4:5], vcc, s[22:23]
	s_and_saveexec_b64 s[38:39], s[4:5]
	s_cbranch_execz .LBB0_3538
	v_lshlrev_b32_e32 v134, 14, v50
	v_lshl_add_u64 v[50:51], s[8:9], 0, v[134:135]
	v_lshlrev_b32_e32 v52, 16, v88
	v_and_b32_e32 v53, 0xffff0000, v88
	v_lshlrev_b32_e32 v54, 16, v89
	v_and_b32_e32 v55, 0xffff0000, v89
	v_pk_add_f32 v[48:49], v[48:49], v[54:55]
	v_pk_add_f32 v[46:47], v[46:47], v[52:53]
	v_lshl_add_u64 v[50:51], v[144:145], 2, v[50:51]
	global_store_dwordx4 v[50:51], v[46:49], off
	s_nop 1
	v_lshlrev_b32_e32 v46, 16, v86
	v_and_b32_e32 v47, 0xffff0000, v86
	v_lshlrev_b32_e32 v48, 16, v87
	v_and_b32_e32 v49, 0xffff0000, v87
	v_pk_add_f32 v[44:45], v[44:45], v[48:49]
	v_pk_add_f32 v[42:43], v[42:43], v[46:47]
	global_store_dwordx4 v[50:51], v[42:45], off offset:64
	s_nop 1
	v_lshlrev_b32_e32 v42, 16, v84
	v_and_b32_e32 v43, 0xffff0000, v84
	v_lshlrev_b32_e32 v44, 16, v85
	v_and_b32_e32 v45, 0xffff0000, v85
	v_pk_add_f32 v[40:41], v[40:41], v[44:45]
	v_pk_add_f32 v[38:39], v[38:39], v[42:43]
	global_store_dwordx4 v[50:51], v[38:41], off offset:512
	s_nop 1
	v_lshlrev_b32_e32 v38, 16, v82
	v_and_b32_e32 v39, 0xffff0000, v82
	v_lshlrev_b32_e32 v40, 16, v83
	v_and_b32_e32 v41, 0xffff0000, v83
	v_pk_add_f32 v[36:37], v[36:37], v[40:41]
	v_pk_add_f32 v[34:35], v[34:35], v[38:39]
	global_store_dwordx4 v[50:51], v[34:37], off offset:576
.LBB0_3538:
	s_or_b64 exec, exec, s[38:39]
	s_nop 0
	v_add_u32_e32 v34, 0xffffff90, v146
	v_cmp_gt_u32_e32 vcc, s55, v34
	s_and_b64 s[4:5], vcc, s[22:23]
	s_and_saveexec_b64 s[38:39], s[4:5]
	s_cbranch_execz .LBB0_3540
	v_lshlrev_b32_e32 v134, 14, v34
	v_lshl_add_u64 v[34:35], s[8:9], 0, v[134:135]
	v_lshlrev_b32_e32 v36, 16, v80
	v_and_b32_e32 v37, 0xffff0000, v80
	v_lshlrev_b32_e32 v38, 16, v81
	v_and_b32_e32 v39, 0xffff0000, v81
	v_pk_add_f32 v[32:33], v[32:33], v[38:39]
	v_pk_add_f32 v[30:31], v[30:31], v[36:37]
	v_lshl_add_u64 v[34:35], v[144:145], 2, v[34:35]
	global_store_dwordx4 v[34:35], v[30:33], off
	s_nop 1
	v_lshlrev_b32_e32 v30, 16, v78
	v_and_b32_e32 v31, 0xffff0000, v78
	v_lshlrev_b32_e32 v32, 16, v79
	v_and_b32_e32 v33, 0xffff0000, v79
	v_pk_add_f32 v[28:29], v[28:29], v[32:33]
	v_pk_add_f32 v[26:27], v[26:27], v[30:31]
	global_store_dwordx4 v[34:35], v[26:29], off offset:64
	s_nop 1
	v_lshlrev_b32_e32 v26, 16, v76
	v_and_b32_e32 v27, 0xffff0000, v76
	v_lshlrev_b32_e32 v28, 16, v77
	v_and_b32_e32 v29, 0xffff0000, v77
	v_pk_add_f32 v[24:25], v[24:25], v[28:29]
	v_pk_add_f32 v[22:23], v[22:23], v[26:27]
	global_store_dwordx4 v[34:35], v[22:25], off offset:512
	s_nop 1
	v_lshlrev_b32_e32 v22, 16, v74
	v_and_b32_e32 v23, 0xffff0000, v74
	v_lshlrev_b32_e32 v24, 16, v75
	v_and_b32_e32 v25, 0xffff0000, v75
	v_pk_add_f32 v[20:21], v[20:21], v[24:25]
	v_pk_add_f32 v[18:19], v[18:19], v[22:23]
	global_store_dwordx4 v[34:35], v[18:21], off offset:576
.LBB0_3540:
	s_or_b64 exec, exec, s[38:39]
	s_nop 0
	v_add_u32_e32 v18, 0xffffffa0, v146
	v_cmp_gt_u32_e32 vcc, s55, v18
	s_and_b64 s[4:5], vcc, s[22:23]
	s_and_saveexec_b64 s[38:39], s[4:5]
	s_cbranch_execz .LBB0_3542
	v_lshlrev_b32_e32 v134, 14, v18
	v_lshl_add_u64 v[18:19], s[8:9], 0, v[134:135]
	v_lshlrev_b32_e32 v20, 16, v72
	v_and_b32_e32 v21, 0xffff0000, v72
	v_lshlrev_b32_e32 v22, 16, v73
	v_and_b32_e32 v23, 0xffff0000, v73
	v_pk_add_f32 v[16:17], v[16:17], v[22:23]
	v_pk_add_f32 v[14:15], v[14:15], v[20:21]
	v_lshl_add_u64 v[18:19], v[144:145], 2, v[18:19]
	global_store_dwordx4 v[18:19], v[14:17], off
	s_nop 1
	v_lshlrev_b32_e32 v14, 16, v70
	v_and_b32_e32 v15, 0xffff0000, v70
	v_lshlrev_b32_e32 v16, 16, v71
	v_and_b32_e32 v17, 0xffff0000, v71
	v_pk_add_f32 v[12:13], v[12:13], v[16:17]
	v_pk_add_f32 v[10:11], v[10:11], v[14:15]
	global_store_dwordx4 v[18:19], v[10:13], off offset:64
	s_nop 1
	v_lshlrev_b32_e32 v10, 16, v68
	v_and_b32_e32 v11, 0xffff0000, v68
	v_lshlrev_b32_e32 v12, 16, v69
	v_and_b32_e32 v13, 0xffff0000, v69
	v_pk_add_f32 v[8:9], v[8:9], v[12:13]
	v_pk_add_f32 v[6:7], v[6:7], v[10:11]
	global_store_dwordx4 v[18:19], v[6:9], off offset:512
	s_nop 1
	v_lshlrev_b32_e32 v6, 16, v66
	v_and_b32_e32 v7, 0xffff0000, v66
	v_lshlrev_b32_e32 v8, 16, v67
	v_and_b32_e32 v9, 0xffff0000, v67
	v_pk_add_f32 v[4:5], v[4:5], v[8:9]
	v_pk_add_f32 v[2:3], v[2:3], v[6:7]
	global_store_dwordx4 v[18:19], v[2:5], off offset:576
